# v20 + grid barrier: every WG (leaders and non-leaders) polls the TOP arrival counter >= (gen+1)*nx directly; TOPGEN/XGEN hops no longer on the critical path
# baseline (speedup 1.0000x reference)
; __device__ __forceinline__ unsigned xb_ld(unsigned* p)              { return __hip_atomic_load(p, __ATOMIC_RELAXED, __HIP_MEMORY_SCOPE_AGENT); }
; __device__ __forceinline__ unsigned xb_add(unsigned* p, unsigned v) { return __hip_atomic_fetch_add(p, v, __ATOMIC_RELAXED, __HIP_MEMORY_SCOPE_AGENT); }
; #define XB_SPIN(cond, bar) do { unsigned _sp = 0; while (cond) { __builtin_amdgcn_s_sleep(1); \
;     if ((++_sp & 255u) == 0u) { if (xb_ld(&(bar)[XB_TMO])) break; if (_sp > XB_SPIN_CAP) { atomicAdd(&(bar)[XB_TMO], 1u); break; } } } } while (0)
; __device__ __forceinline__ void xcd_barrier(const XcdBarrier& b, const int wid) {
;     ...
;         const unsigned old = xb_add(&bar[XB_XSUB(b.x)], 1u);
;         const unsigned gen = old / nloc;
;         if (old + 1u == (gen + 1u) * nloc) {
;             __builtin_amdgcn_fence(__ATOMIC_RELEASE, "agent");
;             asm volatile("s_waitcnt vmcnt(0)" ::: "memory");
;             const unsigned og = xb_add(&bar[XB_TOP], 1u);
;             const unsigned tg = og / nx;
;             if (og + 1u == (tg + 1u) * nx) xb_add(&bar[XB_TOPGEN], 1u);
;             else XB_SPIN(xb_ld(&bar[XB_TOPGEN]) == tg, bar);
;             __builtin_amdgcn_fence(__ATOMIC_ACQUIRE, "agent");
;             xb_add(&bar[XB_XGEN(b.x)], 1u);
;             asm volatile("s_waitcnt vmcnt(0)" ::: "memory");
;         } else {
;             XB_SPIN(xb_ld(&bar[XB_XGEN(b.x)]) == gen, bar);
.LBB0_327:
	s_or_b64 exec, exec, s[12:13]
	v_cvt_f32_u32_e32 v4, v2
	s_waitcnt vmcnt(0)
	v_readfirstlane_b32 s3, v3
	v_sub_u32_e32 v3, 0, v2
	v_rcp_iflag_f32_e32 v4, v4
	v_add_u32_e32 v5, s3, v1
	v_mul_f32_e32 v4, 0x4f7ffffe, v4
	v_cvt_u32_f32_e32 v4, v4
	v_mul_lo_u32 v1, v3, v4
	v_mul_hi_u32 v1, v4, v1
	v_add_u32_e32 v1, v4, v1
	v_mul_hi_u32 v1, v5, v1
	v_mul_lo_u32 v3, v1, v2
	v_sub_u32_e32 v3, v5, v3
	v_add_u32_e32 v4, 1, v1
	v_cmp_ge_u32_e32 vcc, v3, v2
	s_nop 1
	v_cndmask_b32_e32 v1, v1, v4, vcc
	v_sub_u32_e32 v4, v3, v2
	v_cndmask_b32_e32 v3, v3, v4, vcc
	v_add_u32_e32 v4, 1, v1
	v_cmp_ge_u32_e32 vcc, v3, v2
	v_add_u32_e32 v3, 1, v5
	s_nop 0
	v_cndmask_b32_e32 v1, v1, v4, vcc
	v_mul_lo_u32 v4, v2, v1
	v_add_u32_e32 v2, v4, v2
	v_cmp_ne_u32_e32 vcc, v3, v2
	s_and_saveexec_b64 s[10:11], vcc
	s_xor_b64 s[10:11], exec, s[10:11]
	s_cbranch_execz .LBB0_341
	s_waitcnt lgkmcnt(0)
	v_mad_u32_u24 v1, v1, v0, v0
	v_mov_b32_e32 v0, 0x7000
	global_load_dword v0, v0, s[46:47] offset:1024 sc1
	s_add_u32 s16, s46, 0x7400
	s_addc_u32 s17, s47, 0
	s_waitcnt vmcnt(0)
	v_cmp_lt_u32_e32 vcc, v0, v1
	s_and_saveexec_b64 s[12:13], vcc
	s_cbranch_execz .LBB0_340
	s_add_u32 s14, s46, 0x4200
	s_addc_u32 s15, s47, 0
	s_mov_b32 s3, 1
	s_mov_b64 s[18:19], 0
	v_mov_b32_e32 v0, 0
	s_branch .LBB0_331

; __device__ __forceinline__ unsigned xb_ld(unsigned* p)              { return __hip_atomic_load(p, __ATOMIC_RELAXED, __HIP_MEMORY_SCOPE_AGENT); }
; #define XB_SPIN(cond, bar) do { unsigned _sp = 0; while (cond) { __builtin_amdgcn_s_sleep(1); \
;     if ((++_sp & 255u) == 0u) { if (xb_ld(&(bar)[XB_TMO])) break; if (_sp > XB_SPIN_CAP) { atomicAdd(&(bar)[XB_TMO], 1u); break; } } } } while (0)
; __device__ __forceinline__ void xcd_barrier(const XcdBarrier& b, const int wid) {
;     ...
;             XB_SPIN(xb_ld(&bar[XB_XGEN(b.x)]) == gen, bar);
.LBB0_333:
	global_load_dword v2, v0, s[16:17] sc1
	s_add_i32 s3, s3, 1
	s_mov_b64 s[28:29], -1
	s_waitcnt vmcnt(0)
	v_cmp_ge_u32_e32 vcc, v2, v1
	s_orn2_b64 s[26:27], vcc, exec
	s_branch .LBB0_330

; __device__ __forceinline__ unsigned xb_ld(unsigned* p)              { return __hip_atomic_load(p, __ATOMIC_RELAXED, __HIP_MEMORY_SCOPE_AGENT); }
; __device__ __forceinline__ unsigned xb_add(unsigned* p, unsigned v) { return __hip_atomic_fetch_add(p, v, __ATOMIC_RELAXED, __HIP_MEMORY_SCOPE_AGENT); }
; #define XB_SPIN(cond, bar) do { unsigned _sp = 0; while (cond) { __builtin_amdgcn_s_sleep(1); \
;     if ((++_sp & 255u) == 0u) { if (xb_ld(&(bar)[XB_TMO])) break; if (_sp > XB_SPIN_CAP) { atomicAdd(&(bar)[XB_TMO], 1u); break; } } } } while (0)
; __device__ __forceinline__ void xcd_barrier(const XcdBarrier& b, const int wid) {
;     ...
;         const unsigned old = xb_add(&bar[XB_XSUB(b.x)], 1u);
;         const unsigned gen = old / nloc;
;         if (old + 1u == (gen + 1u) * nloc) {
;             __builtin_amdgcn_fence(__ATOMIC_RELEASE, "agent");
;             asm volatile("s_waitcnt vmcnt(0)" ::: "memory");
;             const unsigned og = xb_add(&bar[XB_TOP], 1u);
;             const unsigned tg = og / nx;
;             if (og + 1u == (tg + 1u) * nx) xb_add(&bar[XB_TOPGEN], 1u);
;             else XB_SPIN(xb_ld(&bar[XB_TOPGEN]) == tg, bar);
.LBB0_344:
	s_or_b64 exec, exec, s[12:13]
	v_cvt_f32_u32_e32 v3, v0
	s_waitcnt vmcnt(0)
	v_readfirstlane_b32 s3, v2
	s_add_u32 s12, s46, 0x7500
	s_addc_u32 s13, s47, 0
	v_rcp_iflag_f32_e32 v3, v3
	v_add_u32_e32 v1, s3, v1
	v_add_u32_e32 v4, 1, v1
	s_mov_b64 s[14:15], -1
	v_mul_f32_e32 v2, 0x4f7ffffe, v3
	v_cvt_u32_f32_e32 v2, v2
	v_sub_u32_e32 v3, 0, v0
	v_mul_lo_u32 v3, v3, v2
	v_mul_hi_u32 v3, v2, v3
	v_add_u32_e32 v2, v2, v3
	v_mul_hi_u32 v2, v1, v2
	v_mul_lo_u32 v3, v2, v0
	v_sub_u32_e32 v1, v1, v3
	v_add_u32_e32 v5, 1, v2
	v_cmp_ge_u32_e32 vcc, v1, v0
	v_sub_u32_e32 v3, v1, v0
	s_nop 0
	v_cndmask_b32_e32 v2, v2, v5, vcc
	v_cndmask_b32_e32 v1, v1, v3, vcc
	v_add_u32_e32 v3, 1, v2
	v_cmp_ge_u32_e32 vcc, v1, v0
	s_nop 1
	v_cndmask_b32_e32 v2, v2, v3, vcc
	v_mul_lo_u32 v1, v0, v2
	v_add_u32_e32 v0, v1, v0
	v_cmp_ne_u32_e32 vcc, v4, v0
	v_mov_b32_e32 v2, v0
	v_mov_b64_e32 v[0:1], s[12:13]
	s_and_saveexec_b64 s[10:11], vcc
	s_cbranch_execz .LBB0_356
	v_mov_b32_e32 v0, 0
	global_load_dword v1, v0, s[12:13] offset:-256 sc1
	s_mov_b64 s[18:19], 0
	s_waitcnt vmcnt(0)
	v_cmp_lt_u32_e32 vcc, v1, v2
	s_and_saveexec_b64 s[16:17], vcc
	s_cbranch_execz .LBB0_355
	s_add_u32 s14, s46, 0x4200
	s_addc_u32 s15, s47, 0
	s_mov_b32 s3, 1
	s_branch .LBB0_348

; __device__ __forceinline__ unsigned xb_ld(unsigned* p)              { return __hip_atomic_load(p, __ATOMIC_RELAXED, __HIP_MEMORY_SCOPE_AGENT); }
; #define XB_SPIN(cond, bar) do { unsigned _sp = 0; while (cond) { __builtin_amdgcn_s_sleep(1); \
;     if ((++_sp & 255u) == 0u) { if (xb_ld(&(bar)[XB_TMO])) break; if (_sp > XB_SPIN_CAP) { atomicAdd(&(bar)[XB_TMO], 1u); break; } } } } while (0)
; __device__ __forceinline__ void xcd_barrier(const XcdBarrier& b, const int wid) {
;     ...
;             else XB_SPIN(xb_ld(&bar[XB_TOPGEN]) == tg, bar);
.LBB0_350:
	global_load_dword v1, v0, s[12:13] offset:-256 sc1
	s_add_i32 s3, s3, 1
	s_mov_b64 s[26:27], -1
	s_waitcnt vmcnt(0)
	v_cmp_ge_u32_e32 vcc, v1, v2
	s_orn2_b64 s[30:31], vcc, exec
	s_branch .LBB0_347

; __device__ __forceinline__ unsigned xb_ld(unsigned* p)              { return __hip_atomic_load(p, __ATOMIC_RELAXED, __HIP_MEMORY_SCOPE_AGENT); }
; #define XB_SPIN(cond, bar) do { unsigned _sp = 0; while (cond) { __builtin_amdgcn_s_sleep(1); \
;     if ((++_sp & 255u) == 0u) { if (xb_ld(&(bar)[XB_TMO])) break; if (_sp > XB_SPIN_CAP) { atomicAdd(&(bar)[XB_TMO], 1u); break; } } } } while (0)
; __device__ __forceinline__ void xcd_barrier(const XcdBarrier& b, const int wid) {
;     ...
;             XB_SPIN(xb_ld(&bar[XB_XGEN(b.x)]) == gen, bar);
.LBB0_610:
	global_load_dword v2, v0, s[16:17] sc1
	s_add_i32 s3, s3, 1
	s_mov_b64 s[24:25], -1
	s_waitcnt vmcnt(0)
	v_cmp_ge_u32_e32 vcc, v2, v1
	s_orn2_b64 s[22:23], vcc, exec
	s_branch .LBB0_607

; __device__ __forceinline__ unsigned xb_ld(unsigned* p)              { return __hip_atomic_load(p, __ATOMIC_RELAXED, __HIP_MEMORY_SCOPE_AGENT); }
; #define XB_SPIN(cond, bar) do { unsigned _sp = 0; while (cond) { __builtin_amdgcn_s_sleep(1); \
;     if ((++_sp & 255u) == 0u) { if (xb_ld(&(bar)[XB_TMO])) break; if (_sp > XB_SPIN_CAP) { atomicAdd(&(bar)[XB_TMO], 1u); break; } } } } while (0)
; __device__ __forceinline__ void xcd_barrier(const XcdBarrier& b, const int wid) {
;     ...
;             else XB_SPIN(xb_ld(&bar[XB_TOPGEN]) == tg, bar);
.LBB0_627:
	global_load_dword v1, v0, s[12:13] offset:-256 sc1
	s_add_i32 s3, s3, 1
	s_mov_b64 s[22:23], -1
	s_waitcnt vmcnt(0)
	v_cmp_ge_u32_e32 vcc, v1, v2
	s_orn2_b64 s[26:27], vcc, exec
	s_branch .LBB0_624

; __device__ __forceinline__ unsigned xb_ld(unsigned* p)              { return __hip_atomic_load(p, __ATOMIC_RELAXED, __HIP_MEMORY_SCOPE_AGENT); }
; __device__ __forceinline__ unsigned xb_add(unsigned* p, unsigned v) { return __hip_atomic_fetch_add(p, v, __ATOMIC_RELAXED, __HIP_MEMORY_SCOPE_AGENT); }
; #define XB_SPIN(cond, bar) do { unsigned _sp = 0; while (cond) { __builtin_amdgcn_s_sleep(1); \
;     if ((++_sp & 255u) == 0u) { if (xb_ld(&(bar)[XB_TMO])) break; if (_sp > XB_SPIN_CAP) { atomicAdd(&(bar)[XB_TMO], 1u); break; } } } } while (0)
; __device__ __forceinline__ void xcd_barrier(const XcdBarrier& b, const int wid) {
;     ...
;         const unsigned old = xb_add(&bar[XB_XSUB(b.x)], 1u);
;         const unsigned gen = old / nloc;
;         if (old + 1u == (gen + 1u) * nloc) {
;             __builtin_amdgcn_fence(__ATOMIC_RELEASE, "agent");
;             asm volatile("s_waitcnt vmcnt(0)" ::: "memory");
;             const unsigned og = xb_add(&bar[XB_TOP], 1u);
;             const unsigned tg = og / nx;
;             if (og + 1u == (tg + 1u) * nx) xb_add(&bar[XB_TOPGEN], 1u);
;             else XB_SPIN(xb_ld(&bar[XB_TOPGEN]) == tg, bar);
;             __builtin_amdgcn_fence(__ATOMIC_ACQUIRE, "agent");
;             xb_add(&bar[XB_XGEN(b.x)], 1u);
;             asm volatile("s_waitcnt vmcnt(0)" ::: "memory");
;         } else {
;             XB_SPIN(xb_ld(&bar[XB_XGEN(b.x)]) == gen, bar);
.LBB0_2184:
	s_or_b64 exec, exec, s[14:15]
	v_cvt_f32_u32_e32 v4, v2
	s_waitcnt vmcnt(0)
	v_readfirstlane_b32 s3, v3
	v_sub_u32_e32 v3, 0, v2
	v_rcp_iflag_f32_e32 v4, v4
	v_add_u32_e32 v5, s3, v1
	v_mul_f32_e32 v4, 0x4f7ffffe, v4
	v_cvt_u32_f32_e32 v4, v4
	v_mul_lo_u32 v1, v3, v4
	v_mul_hi_u32 v1, v4, v1
	v_add_u32_e32 v1, v4, v1
	v_mul_hi_u32 v1, v5, v1
	v_mul_lo_u32 v3, v1, v2
	v_sub_u32_e32 v3, v5, v3
	v_add_u32_e32 v4, 1, v1
	v_cmp_ge_u32_e32 vcc, v3, v2
	s_nop 1
	v_cndmask_b32_e32 v1, v1, v4, vcc
	v_sub_u32_e32 v4, v3, v2
	v_cndmask_b32_e32 v3, v3, v4, vcc
	v_add_u32_e32 v4, 1, v1
	v_cmp_ge_u32_e32 vcc, v3, v2
	v_add_u32_e32 v3, 1, v5
	s_nop 0
	v_cndmask_b32_e32 v1, v1, v4, vcc
	v_mul_lo_u32 v4, v2, v1
	v_add_u32_e32 v2, v4, v2
	v_cmp_ne_u32_e32 vcc, v3, v2
	s_and_saveexec_b64 s[12:13], vcc
	s_xor_b64 s[12:13], exec, s[12:13]
	s_cbranch_execz .LBB0_2198
	s_waitcnt lgkmcnt(0)
	v_mad_u32_u24 v1, v1, v0, v0
	v_mov_b32_e32 v0, 0x7000
	global_load_dword v0, v0, s[46:47] offset:1024 sc1
	s_add_u32 s18, s46, 0x7400
	s_addc_u32 s19, s47, 0
	s_waitcnt vmcnt(0)
	v_cmp_lt_u32_e32 vcc, v0, v1
	s_and_saveexec_b64 s[14:15], vcc
	s_cbranch_execz .LBB0_2197
	s_add_u32 s16, s46, 0x4200
	s_addc_u32 s17, s47, 0
	s_mov_b32 s3, 1
	s_mov_b64 s[20:21], 0
	v_mov_b32_e32 v0, 0
	s_branch .LBB0_2188

; __device__ __forceinline__ unsigned xb_ld(unsigned* p)              { return __hip_atomic_load(p, __ATOMIC_RELAXED, __HIP_MEMORY_SCOPE_AGENT); }
; #define XB_SPIN(cond, bar) do { unsigned _sp = 0; while (cond) { __builtin_amdgcn_s_sleep(1); \
;     if ((++_sp & 255u) == 0u) { if (xb_ld(&(bar)[XB_TMO])) break; if (_sp > XB_SPIN_CAP) { atomicAdd(&(bar)[XB_TMO], 1u); break; } } } } while (0)
; __device__ __forceinline__ void xcd_barrier(const XcdBarrier& b, const int wid) {
;     ...
;             XB_SPIN(xb_ld(&bar[XB_XGEN(b.x)]) == gen, bar);
.LBB0_2190:
	global_load_dword v2, v0, s[18:19] sc1
	s_add_i32 s3, s3, 1
	s_mov_b64 s[26:27], -1
	s_waitcnt vmcnt(0)
	v_cmp_ge_u32_e32 vcc, v2, v1
	s_orn2_b64 s[24:25], vcc, exec
	s_branch .LBB0_2187

; __device__ __forceinline__ unsigned xb_ld(unsigned* p)              { return __hip_atomic_load(p, __ATOMIC_RELAXED, __HIP_MEMORY_SCOPE_AGENT); }
; __device__ __forceinline__ unsigned xb_add(unsigned* p, unsigned v) { return __hip_atomic_fetch_add(p, v, __ATOMIC_RELAXED, __HIP_MEMORY_SCOPE_AGENT); }
; #define XB_SPIN(cond, bar) do { unsigned _sp = 0; while (cond) { __builtin_amdgcn_s_sleep(1); \
;     if ((++_sp & 255u) == 0u) { if (xb_ld(&(bar)[XB_TMO])) break; if (_sp > XB_SPIN_CAP) { atomicAdd(&(bar)[XB_TMO], 1u); break; } } } } while (0)
; __device__ __forceinline__ void xcd_barrier(const XcdBarrier& b, const int wid) {
;     ...
;         const unsigned old = xb_add(&bar[XB_XSUB(b.x)], 1u);
;         const unsigned gen = old / nloc;
;         if (old + 1u == (gen + 1u) * nloc) {
;             __builtin_amdgcn_fence(__ATOMIC_RELEASE, "agent");
;             asm volatile("s_waitcnt vmcnt(0)" ::: "memory");
;             const unsigned og = xb_add(&bar[XB_TOP], 1u);
;             const unsigned tg = og / nx;
;             if (og + 1u == (tg + 1u) * nx) xb_add(&bar[XB_TOPGEN], 1u);
;             else XB_SPIN(xb_ld(&bar[XB_TOPGEN]) == tg, bar);
.LBB0_2201:
	s_or_b64 exec, exec, s[14:15]
	v_cvt_f32_u32_e32 v3, v0
	s_waitcnt vmcnt(0)
	v_readfirstlane_b32 s3, v2
	s_add_u32 s14, s46, 0x7500
	s_addc_u32 s15, s47, 0
	v_rcp_iflag_f32_e32 v3, v3
	v_add_u32_e32 v1, s3, v1
	v_add_u32_e32 v4, 1, v1
	s_mov_b64 s[16:17], -1
	v_mul_f32_e32 v2, 0x4f7ffffe, v3
	v_cvt_u32_f32_e32 v2, v2
	v_sub_u32_e32 v3, 0, v0
	v_mul_lo_u32 v3, v3, v2
	v_mul_hi_u32 v3, v2, v3
	v_add_u32_e32 v2, v2, v3
	v_mul_hi_u32 v2, v1, v2
	v_mul_lo_u32 v3, v2, v0
	v_sub_u32_e32 v1, v1, v3
	v_add_u32_e32 v5, 1, v2
	v_cmp_ge_u32_e32 vcc, v1, v0
	v_sub_u32_e32 v3, v1, v0
	s_nop 0
	v_cndmask_b32_e32 v2, v2, v5, vcc
	v_cndmask_b32_e32 v1, v1, v3, vcc
	v_add_u32_e32 v3, 1, v2
	v_cmp_ge_u32_e32 vcc, v1, v0
	s_nop 1
	v_cndmask_b32_e32 v2, v2, v3, vcc
	v_mul_lo_u32 v1, v0, v2
	v_add_u32_e32 v0, v1, v0
	v_cmp_ne_u32_e32 vcc, v4, v0
	v_mov_b32_e32 v2, v0
	v_mov_b64_e32 v[0:1], s[14:15]
	s_and_saveexec_b64 s[12:13], vcc
	s_cbranch_execz .LBB0_2213
	v_mov_b32_e32 v0, 0
	global_load_dword v1, v0, s[14:15] offset:-256 sc1
	s_mov_b64 s[20:21], 0
	s_waitcnt vmcnt(0)
	v_cmp_lt_u32_e32 vcc, v1, v2
	s_and_saveexec_b64 s[18:19], vcc
	s_cbranch_execz .LBB0_2212
	s_add_u32 s16, s46, 0x4200
	s_addc_u32 s17, s47, 0
	s_mov_b32 s3, 1
	s_branch .LBB0_2205

; __device__ __forceinline__ unsigned xb_ld(unsigned* p)              { return __hip_atomic_load(p, __ATOMIC_RELAXED, __HIP_MEMORY_SCOPE_AGENT); }
; #define XB_SPIN(cond, bar) do { unsigned _sp = 0; while (cond) { __builtin_amdgcn_s_sleep(1); \
;     if ((++_sp & 255u) == 0u) { if (xb_ld(&(bar)[XB_TMO])) break; if (_sp > XB_SPIN_CAP) { atomicAdd(&(bar)[XB_TMO], 1u); break; } } } } while (0)
; __device__ __forceinline__ void xcd_barrier(const XcdBarrier& b, const int wid) {
;     ...
;             else XB_SPIN(xb_ld(&bar[XB_TOPGEN]) == tg, bar);
.LBB0_2207:
	global_load_dword v1, v0, s[14:15] offset:-256 sc1
	s_add_i32 s3, s3, 1
	s_mov_b64 s[24:25], -1
	s_waitcnt vmcnt(0)
	v_cmp_ge_u32_e32 vcc, v1, v2
	s_orn2_b64 s[28:29], vcc, exec
	s_branch .LBB0_2204

; __device__ __forceinline__ unsigned xb_ld(unsigned* p)              { return __hip_atomic_load(p, __ATOMIC_RELAXED, __HIP_MEMORY_SCOPE_AGENT); }
; __device__ __forceinline__ unsigned xb_add(unsigned* p, unsigned v) { return __hip_atomic_fetch_add(p, v, __ATOMIC_RELAXED, __HIP_MEMORY_SCOPE_AGENT); }
; #define XB_SPIN(cond, bar) do { unsigned _sp = 0; while (cond) { __builtin_amdgcn_s_sleep(1); \
;     if ((++_sp & 255u) == 0u) { if (xb_ld(&(bar)[XB_TMO])) break; if (_sp > XB_SPIN_CAP) { atomicAdd(&(bar)[XB_TMO], 1u); break; } } } } while (0)
; __device__ __forceinline__ void xcd_barrier(const XcdBarrier& b, const int wid) {
;     ...
;         const unsigned old = xb_add(&bar[XB_XSUB(b.x)], 1u);
;         const unsigned gen = old / nloc;
;         if (old + 1u == (gen + 1u) * nloc) {
;             __builtin_amdgcn_fence(__ATOMIC_RELEASE, "agent");
;             asm volatile("s_waitcnt vmcnt(0)" ::: "memory");
;             const unsigned og = xb_add(&bar[XB_TOP], 1u);
;             const unsigned tg = og / nx;
;             if (og + 1u == (tg + 1u) * nx) xb_add(&bar[XB_TOPGEN], 1u);
;             else XB_SPIN(xb_ld(&bar[XB_TOPGEN]) == tg, bar);
;             __builtin_amdgcn_fence(__ATOMIC_ACQUIRE, "agent");
;             xb_add(&bar[XB_XGEN(b.x)], 1u);
;             asm volatile("s_waitcnt vmcnt(0)" ::: "memory");
;         } else {
;             XB_SPIN(xb_ld(&bar[XB_XGEN(b.x)]) == gen, bar);
.LBB0_2567:
	s_or_b64 exec, exec, s[10:11]
	v_cvt_f32_u32_e32 v4, v2
	s_waitcnt vmcnt(0)
	v_readfirstlane_b32 s8, v3
	v_sub_u32_e32 v3, 0, v2
	v_rcp_iflag_f32_e32 v4, v4
	v_add_u32_e32 v5, s8, v1
	v_mul_f32_e32 v4, 0x4f7ffffe, v4
	v_cvt_u32_f32_e32 v4, v4
	v_mul_lo_u32 v1, v3, v4
	v_mul_hi_u32 v1, v4, v1
	v_add_u32_e32 v1, v4, v1
	v_mul_hi_u32 v1, v5, v1
	v_mul_lo_u32 v3, v1, v2
	v_sub_u32_e32 v3, v5, v3
	v_add_u32_e32 v4, 1, v1
	v_cmp_ge_u32_e32 vcc, v3, v2
	s_nop 1
	v_cndmask_b32_e32 v1, v1, v4, vcc
	v_sub_u32_e32 v4, v3, v2
	v_cndmask_b32_e32 v3, v3, v4, vcc
	v_add_u32_e32 v4, 1, v1
	v_cmp_ge_u32_e32 vcc, v3, v2
	v_add_u32_e32 v3, 1, v5
	s_nop 0
	v_cndmask_b32_e32 v1, v1, v4, vcc
	v_mul_lo_u32 v4, v2, v1
	v_add_u32_e32 v2, v4, v2
	v_cmp_ne_u32_e32 vcc, v3, v2
	s_and_saveexec_b64 s[8:9], vcc
	s_xor_b64 s[8:9], exec, s[8:9]
	s_cbranch_execz .LBB0_2581
	s_waitcnt lgkmcnt(0)
	v_mad_u32_u24 v1, v1, v0, v0
	v_mov_b32_e32 v0, 0x7000
	global_load_dword v0, v0, s[46:47] offset:1024 sc1
	s_add_u32 s14, s46, 0x7400
	s_addc_u32 s15, s47, 0
	s_waitcnt vmcnt(0)
	v_cmp_lt_u32_e32 vcc, v0, v1
	s_and_saveexec_b64 s[10:11], vcc
	s_cbranch_execz .LBB0_2580
	s_add_u32 s12, s46, 0x4200
	s_addc_u32 s13, s47, 0
	s_mov_b32 s26, 1
	s_mov_b64 s[16:17], 0
	v_mov_b32_e32 v0, 0
	s_branch .LBB0_2571

; __device__ __forceinline__ unsigned xb_ld(unsigned* p)              { return __hip_atomic_load(p, __ATOMIC_RELAXED, __HIP_MEMORY_SCOPE_AGENT); }
; #define XB_SPIN(cond, bar) do { unsigned _sp = 0; while (cond) { __builtin_amdgcn_s_sleep(1); \
;     if ((++_sp & 255u) == 0u) { if (xb_ld(&(bar)[XB_TMO])) break; if (_sp > XB_SPIN_CAP) { atomicAdd(&(bar)[XB_TMO], 1u); break; } } } } while (0)
; __device__ __forceinline__ void xcd_barrier(const XcdBarrier& b, const int wid) {
;     ...
;             XB_SPIN(xb_ld(&bar[XB_XGEN(b.x)]) == gen, bar);
.LBB0_2573:
	global_load_dword v2, v0, s[14:15] sc1
	s_add_i32 s26, s26, 1
	s_mov_b64 s[22:23], -1
	s_waitcnt vmcnt(0)
	v_cmp_ge_u32_e32 vcc, v2, v1
	s_orn2_b64 s[20:21], vcc, exec
	s_branch .LBB0_2570

; __device__ __forceinline__ unsigned xb_ld(unsigned* p)              { return __hip_atomic_load(p, __ATOMIC_RELAXED, __HIP_MEMORY_SCOPE_AGENT); }
; __device__ __forceinline__ unsigned xb_add(unsigned* p, unsigned v) { return __hip_atomic_fetch_add(p, v, __ATOMIC_RELAXED, __HIP_MEMORY_SCOPE_AGENT); }
; #define XB_SPIN(cond, bar) do { unsigned _sp = 0; while (cond) { __builtin_amdgcn_s_sleep(1); \
;     if ((++_sp & 255u) == 0u) { if (xb_ld(&(bar)[XB_TMO])) break; if (_sp > XB_SPIN_CAP) { atomicAdd(&(bar)[XB_TMO], 1u); break; } } } } while (0)
; __device__ __forceinline__ void xcd_barrier(const XcdBarrier& b, const int wid) {
;     ...
;         const unsigned old = xb_add(&bar[XB_XSUB(b.x)], 1u);
;         const unsigned gen = old / nloc;
;         if (old + 1u == (gen + 1u) * nloc) {
;             __builtin_amdgcn_fence(__ATOMIC_RELEASE, "agent");
;             asm volatile("s_waitcnt vmcnt(0)" ::: "memory");
;             const unsigned og = xb_add(&bar[XB_TOP], 1u);
;             const unsigned tg = og / nx;
;             if (og + 1u == (tg + 1u) * nx) xb_add(&bar[XB_TOPGEN], 1u);
;             else XB_SPIN(xb_ld(&bar[XB_TOPGEN]) == tg, bar);
.LBB0_2584:
	s_or_b64 exec, exec, s[10:11]
	v_cvt_f32_u32_e32 v3, v0
	s_waitcnt vmcnt(0)
	v_readfirstlane_b32 s8, v2
	s_add_u32 s10, s46, 0x7500
	s_addc_u32 s11, s47, 0
	v_rcp_iflag_f32_e32 v3, v3
	v_add_u32_e32 v1, s8, v1
	v_add_u32_e32 v4, 1, v1
	s_mov_b64 s[12:13], -1
	v_mul_f32_e32 v2, 0x4f7ffffe, v3
	v_cvt_u32_f32_e32 v2, v2
	v_sub_u32_e32 v3, 0, v0
	v_mul_lo_u32 v3, v3, v2
	v_mul_hi_u32 v3, v2, v3
	v_add_u32_e32 v2, v2, v3
	v_mul_hi_u32 v2, v1, v2
	v_mul_lo_u32 v3, v2, v0
	v_sub_u32_e32 v1, v1, v3
	v_add_u32_e32 v5, 1, v2
	v_cmp_ge_u32_e32 vcc, v1, v0
	v_sub_u32_e32 v3, v1, v0
	s_nop 0
	v_cndmask_b32_e32 v2, v2, v5, vcc
	v_cndmask_b32_e32 v1, v1, v3, vcc
	v_add_u32_e32 v3, 1, v2
	v_cmp_ge_u32_e32 vcc, v1, v0
	s_nop 1
	v_cndmask_b32_e32 v2, v2, v3, vcc
	v_mul_lo_u32 v1, v0, v2
	v_add_u32_e32 v0, v1, v0
	v_cmp_ne_u32_e32 vcc, v4, v0
	v_mov_b32_e32 v2, v0
	v_mov_b64_e32 v[0:1], s[10:11]
	s_and_saveexec_b64 s[8:9], vcc
	s_cbranch_execz .LBB0_2596
	v_mov_b32_e32 v0, 0
	global_load_dword v1, v0, s[10:11] offset:-256 sc1
	s_mov_b64 s[16:17], 0
	s_waitcnt vmcnt(0)
	v_cmp_lt_u32_e32 vcc, v1, v2
	s_and_saveexec_b64 s[14:15], vcc
	s_cbranch_execz .LBB0_2595
	s_add_u32 s12, s46, 0x4200
	s_addc_u32 s13, s47, 0
	s_mov_b32 s26, 1
	s_branch .LBB0_2588

; __device__ __forceinline__ unsigned xb_ld(unsigned* p)              { return __hip_atomic_load(p, __ATOMIC_RELAXED, __HIP_MEMORY_SCOPE_AGENT); }
; #define XB_SPIN(cond, bar) do { unsigned _sp = 0; while (cond) { __builtin_amdgcn_s_sleep(1); \
;     if ((++_sp & 255u) == 0u) { if (xb_ld(&(bar)[XB_TMO])) break; if (_sp > XB_SPIN_CAP) { atomicAdd(&(bar)[XB_TMO], 1u); break; } } } } while (0)
; __device__ __forceinline__ void xcd_barrier(const XcdBarrier& b, const int wid) {
;     ...
;             else XB_SPIN(xb_ld(&bar[XB_TOPGEN]) == tg, bar);
.LBB0_2590:
	global_load_dword v1, v0, s[10:11] offset:-256 sc1
	s_add_i32 s26, s26, 1
	s_mov_b64 s[20:21], -1
	s_waitcnt vmcnt(0)
	v_cmp_ge_u32_e32 vcc, v1, v2
	s_orn2_b64 s[24:25], vcc, exec
	s_branch .LBB0_2587
